# attention: next q-block's Q fragments loaded right after the last tile's QK MFMAs (one tile earlier), tail/transition waits rebased by the 6 extra loads
# baseline (speedup 1.0000x reference)
.Latt_sk3:
	s_or_b64 exec, exec, s[46:47]
	v_add_u32_e32 v120, s5, v14
	v_add_u32_e32 v184, s5, v15
	v_min_u32_e32 v120, 0x80ff, v120
	v_add_u32_e32 v186, 1, v184
	v_min_u32_e32 v184, 0x80ff, v184
	v_min_u32_e32 v186, 0x80ff, v186
	v_lshl_add_u32 v122, v120, 12, v238
	v_lshl_add_u32 v124, v120, 6, v239
	v_lshl_add_u32 v184, v184, 12, v174
	v_lshl_add_u32 v186, v186, 12, v174
	global_load_dwordx4 v[120:123], v122, s[98:99]
	s_nop 0
	global_load_dwordx4 v[124:127], v124, s[100:101]
	global_load_dwordx2 v[184:185], v184, s[98:99] offset:128
	global_load_dwordx2 v[186:187], v186, s[98:99] offset:128
	s_cmp_eq_u32 s32, 0
	s_cbranch_scc1 .Lqp_skip_s3
	v_add_u32_e32 v156, s56, v215
	v_mad_u32_u24 v156, v156, s90, v176
	s_add_u32 s4, s48, s86
	s_addc_u32 s5, s49, 0
	s_add_u32 s6, s48, s78
	s_addc_u32 s7, s49, 0
	global_load_dwordx4 v[96:99], v156, s[4:5] nt
	global_load_dwordx4 v[100:103], v156, s[4:5] offset:32 nt
	global_load_dwordx4 v[104:107], v156, s[4:5] offset:64 nt
	global_load_dwordx4 v[108:111], v156, s[4:5] offset:96 nt
	global_load_dwordx4 v[112:115], v156, s[6:7] offset:2048 nt
	global_load_dwordx4 v[116:119], v156, s[6:7] offset:2080 nt
.Lqp_skip_s3:
	s_branch .LBB0_451
.Latt_sk2:
	s_or_b64 exec, exec, s[44:45]
	v_min_u32_e32 v120, 0x80ff, v120
	v_add_u32_e32 v186, 1, v184
	v_min_u32_e32 v184, 0x80ff, v184
	v_min_u32_e32 v186, 0x80ff, v186
	v_lshl_add_u32 v122, v120, 12, v238
	v_lshl_add_u32 v124, v120, 6, v239
	v_lshl_add_u32 v184, v184, 12, v174
	v_lshl_add_u32 v186, v186, 12, v174
	global_load_dwordx4 v[120:123], v122, s[98:99]
	s_nop 0
	global_load_dwordx4 v[124:127], v124, s[100:101]
	global_load_dwordx2 v[184:185], v184, s[98:99] offset:128
	global_load_dwordx2 v[186:187], v186, s[98:99] offset:128
	s_branch .LBB0_437
.Latt_sk1:
	s_or_b64 exec, exec, s[46:47]
	s_waitcnt vmcnt(3)
	v_add_u32_e32 v2, s5, v221
	v_add_u32_e32 v14, s5, v222
	v_min_u32_e32 v2, 0x80ff, v2
	v_add_u32_e32 v192, 1, v14
	v_min_u32_e32 v14, 0x80ff, v14
	v_min_u32_e32 v192, 0x80ff, v192
	v_lshl_add_u32 v4, v2, 12, v238
	s_waitcnt vmcnt(2)
	v_lshl_add_u32 v6, v2, 6, v239
	v_lshl_add_u32 v14, v14, 12, v174
	v_lshl_add_u32 v192, v192, 12, v174
	global_load_dwordx4 v[2:5], v4, s[98:99]
	s_nop 0
	global_load_dwordx4 v[6:9], v6, s[100:101]
	global_load_dwordx2 v[14:15], v14, s[98:99] offset:128
	global_load_dwordx2 v[192:193], v192, s[98:99] offset:128
	s_cmp_eq_u32 s32, 0
	s_cbranch_scc1 .Lqp_skip_s1
	v_add_u32_e32 v223, s56, v215
	v_mad_u32_u24 v223, v223, s90, v176
	s_add_u32 s4, s48, s86
	s_addc_u32 s5, s49, 0
	s_add_u32 s6, s48, s78
	s_addc_u32 s7, s49, 0
	global_load_dwordx4 v[96:99], v223, s[4:5] nt
	global_load_dwordx4 v[100:103], v223, s[4:5] offset:32 nt
	global_load_dwordx4 v[104:107], v223, s[4:5] offset:64 nt
	global_load_dwordx4 v[108:111], v223, s[4:5] offset:96 nt
	global_load_dwordx4 v[112:115], v223, s[6:7] offset:2048 nt
	global_load_dwordx4 v[116:119], v223, s[6:7] offset:2080 nt
.Lqp_skip_s1:
	s_branch .LBB0_426
.LBB0_416:
	s_or_b64 exec, exec, s[4:5]
	s_waitcnt vmcnt(4)
	v_perm_b32 v10, v192, v14, s94
	v_perm_b32 v11, v192, v14, s95
	ds_write2_b32 v254, v10, v11 offset0:128 offset1:162
	v_perm_b32 v10, v193, v15, s94
	v_perm_b32 v11, v193, v15, s95
	ds_write2_b32 v254, v10, v11 offset0:196 offset1:230
	s_waitcnt lgkmcnt(0)
	s_barrier

; #define LAS __attribute__((address_space(3)))
; __device__ __forceinline__ void qk_tile(f32x16& s0, f32x16& s1, LAS unsigned char* kb, const bf16x8 (&qr)[6], const f32x16& negm, int r32, int hi) {
;     bf16x8 kf[12];
; #pragma unroll
;     for (int ks = 0; ks < 6; ++ks) { kf[2 * ks] = *(const LAS bf16x8*)(kb + r32 * KPT + ks * 32 + hi * 16); kf[2 * ks + 1] = *(const LAS bf16x8*)(kb + (32 + r32) * KPT + ks * 32 + hi * 16); }
;     __builtin_amdgcn_sched_barrier(0);
; #pragma unroll
;     for (int ks = 0; ks < 6; ++ks) {
;         s0 = __builtin_amdgcn_mfma_f32_32x32x16_bf16(kf[2 * ks], qr[ks], ks == 0 ? negm : s0, 0, 0, 0);
;         s1 = __builtin_amdgcn_mfma_f32_32x32x16_bf16(kf[2 * ks + 1], qr[ks], ks == 0 ? negm : s1, 0, 0, 0);
;     }
.LBB0_418:
	s_add_i32 s85, s84, -3
	s_cmp_lt_u32 s85, s57
	s_cselect_b64 s[44:45], -1, 0
	s_cselect_b32 s32, 0, 1
	s_cmp_eq_u32 s43, 8
	s_cselect_b32 s32, 0, s32
	s_and_b64 s[4:5], s[44:45], exec
	s_cselect_b32 s4, 0, s79
	s_lshl_b32 s4, s4, 6
	v_add_u32_e32 v221, s83, v213
	v_add_u32_e32 v222, s83, v173
	s_sub_i32 s5, 0x80, s4
	v_cmp_le_u32_e32 vcc, s83, v220
	s_and_saveexec_b64 s[46:47], vcc
	s_cbranch_execz .Latt_sk1
	ds_read_b128 v[10:13], v240 offset:13312
	ds_read_b128 v[136:139], v240 offset:13344
	ds_read_b128 v[140:143], v240 offset:19968
	ds_read_b128 v[144:147], v240 offset:20000
	ds_read_b128 v[148:151], v240 offset:13376
	ds_read_b128 v[152:155], v240 offset:13408
	ds_read_b128 v[156:159], v240 offset:20032
	ds_read_b128 v[160:163], v240 offset:20064
	ds_read_b128 v[224:227], v240 offset:13440
	ds_read_b128 v[228:231], v240 offset:13472
	ds_read_b128 v[232:235], v240 offset:20096
	ds_read_b128 v[246:249], v240 offset:20128
	s_waitcnt lgkmcnt(11)
	v_mfma_f32_32x32x16_bf16 v[80:95], v[10:13], v[96:99], v[48:63]
	s_add_i32 s4, s83, 63
	v_cmp_gt_i32_e32 vcc, s4, v175
	s_waitcnt lgkmcnt(9)
	v_mfma_f32_32x32x16_bf16 v[64:79], v[140:143], v[96:99], v[48:63]
	v_mfma_f32_32x32x16_bf16 v[80:95], v[136:139], v[100:103], v[80:95]
	s_waitcnt lgkmcnt(8)
	v_mfma_f32_32x32x16_bf16 v[64:79], v[144:147], v[100:103], v[64:79]
	s_waitcnt lgkmcnt(7)
	v_mfma_f32_32x32x16_bf16 v[80:95], v[148:151], v[104:107], v[80:95]
	s_waitcnt lgkmcnt(5)
	v_mfma_f32_32x32x16_bf16 v[64:79], v[156:159], v[104:107], v[64:79]
	v_mfma_f32_32x32x16_bf16 v[80:95], v[152:155], v[108:111], v[80:95]
	ds_read2_b64 v[152:155], v250 offset0:68 offset1:70
	s_waitcnt lgkmcnt(5)
	v_mfma_f32_32x32x16_bf16 v[64:79], v[160:163], v[108:111], v[64:79]
	ds_read2_b64 v[160:163], v250 offset0:64 offset1:66
	ds_read2_b64 v[156:159], v251 offset0:96 offset1:98
	ds_read2_b64 v[148:151], v251 offset0:100 offset1:102
	ds_read2_b64 v[144:147], v250 offset0:72 offset1:74
	ds_read2_b64 v[140:143], v251 offset0:104 offset1:106
	ds_read2_b64 v[136:139], v250 offset0:76 offset1:78
	ds_read2_b64 v[10:13], v251 offset0:108 offset1:110
	s_waitcnt lgkmcnt(11)
	v_mfma_f32_32x32x16_bf16 v[80:95], v[224:227], v[112:115], v[80:95]
	s_waitcnt lgkmcnt(9)
	v_mfma_f32_32x32x16_bf16 v[64:79], v[232:235], v[112:115], v[64:79]
	v_mfma_f32_32x32x16_bf16 v[80:95], v[228:231], v[116:119], v[80:95]
	s_waitcnt lgkmcnt(8)
	v_mfma_f32_32x32x16_bf16 v[64:79], v[246:249], v[116:119], v[64:79]
	s_waitcnt vmcnt(3)
	v_add_u32_e32 v2, s5, v221
	v_add_u32_e32 v14, s5, v222
	v_min_u32_e32 v2, 0x80ff, v2
	v_add_u32_e32 v192, 1, v14
	v_min_u32_e32 v14, 0x80ff, v14
	v_min_u32_e32 v192, 0x80ff, v192
	v_lshl_add_u32 v4, v2, 12, v238
	s_waitcnt vmcnt(2)
	v_lshl_add_u32 v6, v2, 6, v239
	v_lshl_add_u32 v14, v14, 12, v174
	v_lshl_add_u32 v192, v192, 12, v174
	global_load_dwordx4 v[2:5], v4, s[98:99]
	s_nop 0
	global_load_dwordx4 v[6:9], v6, s[100:101]
	global_load_dwordx2 v[14:15], v14, s[98:99] offset:128
	global_load_dwordx2 v[192:193], v192, s[98:99] offset:128
	s_cmp_eq_u32 s32, 0
	s_cbranch_scc1 .Lqp_skip_a1
	v_add_u32_e32 v223, s56, v215
	v_mad_u32_u24 v223, v223, s90, v176
	s_add_u32 s4, s48, s86
	s_addc_u32 s5, s49, 0
	s_add_u32 s6, s48, s78
	s_addc_u32 s7, s49, 0
	global_load_dwordx4 v[96:99], v223, s[4:5] nt
	global_load_dwordx4 v[100:103], v223, s[4:5] offset:32 nt
	global_load_dwordx4 v[104:107], v223, s[4:5] offset:64 nt
	global_load_dwordx4 v[108:111], v223, s[4:5] offset:96 nt
	global_load_dwordx4 v[112:115], v223, s[6:7] offset:2048 nt
	global_load_dwordx4 v[116:119], v223, s[6:7] offset:2080 nt
; __device__ __forceinline__ void sm_pv(f32x16& s0, f32x16& s1, f32x16& o0, f32x16& o1, float& m_run, float& l_run, f32x16& negm, LAS unsigned char* vb, bool domask, int kbase, int qm, int r32, int hi) {
;     ...
;     if (domask) {
;         const int kb0 = kbase + 4 * hi;
; #pragma unroll
;         for (int r = 0; r < 16; ++r) { const int kv = kb0 + (r & 3) + 8 * (r >> 2); if (kv > qm) s0[r] = -INFINITY; if (kv + 32 > qm) s1[r] = -INFINITY; }
;     }
.Lqp_skip_a1:
	s_and_saveexec_b64 s[58:59], vcc
	s_cbranch_execz .LBB0_423
	v_add_u32_e32 v223, s83, v201
	v_add_u32_e32 v224, 32, v223
	v_cmp_ge_i32_e64 s[4:5], v177, v224
	v_add_u32_e32 v224, 33, v223
	v_cmp_ge_i32_e64 s[6:7], v177, v224
	v_add_u32_e32 v224, 2, v223
	v_cmp_le_u32_e32 vcc, v223, v219
	s_nop 2
	v_cndmask_b32_e64 v65, v244, v65, s[6:7]
	v_cmp_ge_i32_e64 s[6:7], v177, v224
	v_add_u32_e32 v224, 34, v223
	v_cmp_ge_i32_e64 s[8:9], v177, v224
	v_add_u32_e32 v224, 3, v223
	v_cndmask_b32_e64 v64, v244, v64, s[4:5]
	v_cndmask_b32_e64 v66, v244, v66, s[8:9]
	v_cmp_ge_i32_e64 s[8:9], v177, v224
	v_add_u32_e32 v224, 35, v223
	v_cmp_ge_i32_e64 s[10:11], v177, v224
	v_add_u32_e32 v224, 8, v223
	v_cmp_gt_i32_e64 s[4:5], v177, v223
	v_cndmask_b32_e64 v67, v244, v67, s[10:11]
	v_cmp_ge_i32_e64 s[10:11], v177, v224
	v_add_u32_e32 v224, 40, v223
	v_cmp_ge_i32_e64 s[12:13], v177, v224
	v_add_u32_e32 v224, 9, v223
	s_nop 0
	v_cndmask_b32_e64 v68, v244, v68, s[12:13]
	v_cmp_ge_i32_e64 s[12:13], v177, v224
	v_add_u32_e32 v224, 41, v223
	v_cmp_ge_i32_e64 s[14:15], v177, v224
	v_add_u32_e32 v224, 10, v223
	s_nop 0
	v_cndmask_b32_e64 v69, v244, v69, s[14:15]
	v_cmp_ge_i32_e64 s[14:15], v177, v224
	v_add_u32_e32 v224, 42, v223
	v_cmp_ge_i32_e64 s[16:17], v177, v224
	v_add_u32_e32 v224, 11, v223
	s_nop 0
	v_cndmask_b32_e64 v70, v244, v70, s[16:17]
	v_cmp_ge_i32_e64 s[16:17], v177, v224
	v_add_u32_e32 v224, 43, v223
	v_cmp_ge_i32_e64 s[18:19], v177, v224
	v_add_u32_e32 v224, 16, v223
	s_nop 0
	v_cndmask_b32_e64 v71, v244, v71, s[18:19]
	v_cmp_ge_i32_e64 s[18:19], v177, v224
	v_add_u32_e32 v224, 48, v223
	v_cmp_ge_i32_e64 s[20:21], v177, v224
	v_add_u32_e32 v224, 17, v223
	s_nop 0
	v_cndmask_b32_e64 v72, v244, v72, s[20:21]
	v_cmp_ge_i32_e64 s[20:21], v177, v224
	v_add_u32_e32 v224, 49, v223
	v_cmp_ge_i32_e64 s[22:23], v177, v224
	v_add_u32_e32 v224, 18, v223
	s_nop 0
	v_cndmask_b32_e64 v73, v244, v73, s[22:23]
	v_cmp_ge_i32_e64 s[22:23], v177, v224
	v_add_u32_e32 v224, 50, v223
	v_cmp_ge_i32_e64 s[24:25], v177, v224
	v_add_u32_e32 v224, 19, v223
	s_nop 0
	v_cndmask_b32_e64 v74, v244, v74, s[24:25]
	v_cmp_ge_i32_e64 s[24:25], v177, v224
	v_add_u32_e32 v224, 51, v223
	v_cmp_ge_i32_e64 s[26:27], v177, v224
	v_add_u32_e32 v224, 24, v223
	s_nop 0
	v_cndmask_b32_e64 v75, v244, v75, s[26:27]
	v_cmp_ge_i32_e64 s[26:27], v177, v224
	v_add_u32_e32 v224, 56, v223
	v_cmp_ge_i32_e64 s[28:29], v177, v224
	v_add_u32_e32 v224, 25, v223
	s_nop 0
	v_cndmask_b32_e64 v76, v244, v76, s[28:29]
	v_cmp_ge_i32_e64 s[28:29], v177, v224
	v_add_u32_e32 v224, 57, v223
	v_cmp_ge_i32_e64 s[30:31], v177, v224
	v_add_u32_e32 v224, 26, v223
	s_nop 0
	v_cndmask_b32_e64 v77, v244, v77, s[30:31]
	v_cmp_ge_i32_e64 s[30:31], v177, v224
	v_add_u32_e32 v224, 58, v223
	v_cmp_ge_i32_e64 s[34:35], v177, v224
	v_add_u32_e32 v224, 27, v223
	v_add_u32_e32 v223, 59, v223
	v_cndmask_b32_e64 v78, v244, v78, s[34:35]
	v_cmp_ge_i32_e64 s[34:35], v177, v224
	v_cmp_lt_i32_e64 s[36:37], v177, v223
	s_and_saveexec_b64 s[40:41], s[36:37]
	v_mov_b32_e32 v79, s52
	s_or_b64 exec, exec, s[40:41]
	v_cndmask_b32_e32 v80, v244, v80, vcc
	v_cndmask_b32_e64 v81, v244, v81, s[4:5]
	v_cndmask_b32_e64 v82, v244, v82, s[6:7]
	v_cndmask_b32_e64 v83, v244, v83, s[8:9]
	v_cndmask_b32_e64 v84, v244, v84, s[10:11]
	v_cndmask_b32_e64 v85, v244, v85, s[12:13]
	v_cndmask_b32_e64 v86, v244, v86, s[14:15]
	v_cndmask_b32_e64 v87, v244, v87, s[16:17]
	v_cndmask_b32_e64 v88, v244, v88, s[18:19]
	v_cndmask_b32_e64 v89, v244, v89, s[20:21]
	v_cndmask_b32_e64 v90, v244, v90, s[22:23]
	v_cndmask_b32_e64 v91, v244, v91, s[24:25]
	v_cndmask_b32_e64 v92, v244, v92, s[26:27]
	v_cndmask_b32_e64 v93, v244, v93, s[28:29]
	v_cndmask_b32_e64 v94, v244, v94, s[30:31]
	v_cndmask_b32_e64 v95, v244, v95, s[34:35]

.LBB0_426:
	s_or_b64 exec, exec, s[46:47]
	ds_write_b128 v210, v[120:123]
	s_and_saveexec_b64 s[4:5], s[2:3]
	ds_write_b128 v210, v[124:127] offset:128
	s_or_b64 exec, exec, s[4:5]
	s_cmp_eq_u32 s32, 0
	s_cbranch_scc1 .Lqw_t1_n
	s_waitcnt vmcnt(10)
	s_branch .Lqw_t1_j
.Lqw_t1_n:
	s_waitcnt vmcnt(4)
; #define LAS __attribute__((address_space(3)))
; __device__ __forceinline__ void qk_tile(f32x16& s0, f32x16& s1, LAS unsigned char* kb, const bf16x8 (&qr)[6], const f32x16& negm, int r32, int hi) {
;     bf16x8 kf[12];
; #pragma unroll
;     for (int ks = 0; ks < 6; ++ks) { kf[2 * ks] = *(const LAS bf16x8*)(kb + r32 * KPT + ks * 32 + hi * 16); kf[2 * ks + 1] = *(const LAS bf16x8*)(kb + (32 + r32) * KPT + ks * 32 + hi * 16); }
;     __builtin_amdgcn_sched_barrier(0);
; #pragma unroll
;     for (int ks = 0; ks < 6; ++ks) {
;         s0 = __builtin_amdgcn_mfma_f32_32x32x16_bf16(kf[2 * ks], qr[ks], ks == 0 ? negm : s0, 0, 0, 0);
;         s1 = __builtin_amdgcn_mfma_f32_32x32x16_bf16(kf[2 * ks + 1], qr[ks], ks == 0 ? negm : s1, 0, 0, 0);
;     }
; }
; __device__ __forceinline__ void sm_pv(f32x16& s0, f32x16& s1, f32x16& o0, f32x16& o1, float& m_run, float& l_run, f32x16& negm, LAS unsigned char* vb, bool domask, int kbase, int qm, int r32, int hi) {
;     s16x4 vlo[8], vhh[8];
; #pragma unroll
;     for (int kk = 0; kk < 4; ++kk) { const int koff = 2 * (16 * kk + 4 * hi);
;         vlo[2 * kk] = *(const LAS s16x4*)(vb + r32 * VP + koff); vhh[2 * kk] = *(const LAS s16x4*)(vb + r32 * VP + koff + 16);
;         vlo[2 * kk + 1] = *(const LAS s16x4*)(vb + (32 + r32) * VP + koff); vhh[2 * kk + 1] = *(const LAS s16x4*)(vb + (32 + r32) * VP + koff + 16); }
;     __builtin_amdgcn_sched_barrier(0);
;     if (domask) {
;         const int kb0 = kbase + 4 * hi;
; #pragma unroll
;         for (int r = 0; r < 16; ++r) { const int kv = kb0 + (r & 3) + 8 * (r >> 2); if (kv > qm) s0[r] = -INFINITY; if (kv + 32 > qm) s1[r] = -INFINITY; }
;     }
.Lqw_t1_j:
	v_perm_b32 v10, v186, v184, s94
	v_perm_b32 v11, v186, v184, s95
	ds_write2_b32 v214, v10, v11 offset1:34
	v_perm_b32 v10, v187, v185, s94
	v_perm_b32 v11, v187, v185, s95
	ds_write2_b32 v214, v10, v11 offset0:68 offset1:102
	s_waitcnt lgkmcnt(0)
	s_barrier
	s_andn2_b64 vcc, exec, s[44:45]
	s_cbranch_vccnz .LBB0_417
	s_cmp_gt_u32 s84, s57
	s_cselect_b32 s4, s79, 0
	s_lshl_b32 s4, s4, 6
	s_sub_i32 s5, 0xc0, s4
	v_add_u32_e32 v120, s5, v221
	v_add_u32_e32 v184, s5, v222
	s_add_i32 s4, s83, 64
	v_cmp_le_u32_e32 vcc, s4, v220
	s_and_saveexec_b64 s[44:45], vcc
	s_cbranch_execz .Latt_sk2
	ds_read_b128 v[10:13], v241
	ds_read_b128 v[136:139], v241 offset:32
	ds_read_b128 v[140:143], v241 offset:6656
	ds_read_b128 v[144:147], v241 offset:6688
	ds_read_b128 v[148:151], v241 offset:64
	ds_read_b128 v[152:155], v241 offset:96
	ds_read_b128 v[156:159], v241 offset:6720
	ds_read_b128 v[160:163], v241 offset:6752
	ds_read_b128 v[222:225], v241 offset:128
	ds_read_b128 v[226:229], v241 offset:160
	ds_read_b128 v[230:233], v241 offset:6784
	ds_read_b128 v[234:237], v241 offset:6816
	s_waitcnt lgkmcnt(11)
	v_mfma_f32_32x32x16_bf16 v[80:95], v[10:13], v[96:99], v[48:63]
	s_add_i32 s4, s83, 0x7f
	v_cmp_gt_i32_e32 vcc, s4, v175
	s_waitcnt lgkmcnt(9)
	v_mfma_f32_32x32x16_bf16 v[64:79], v[140:143], v[96:99], v[48:63]
	v_mfma_f32_32x32x16_bf16 v[80:95], v[136:139], v[100:103], v[80:95]
	s_waitcnt lgkmcnt(8)
	v_mfma_f32_32x32x16_bf16 v[64:79], v[144:147], v[100:103], v[64:79]
	s_waitcnt lgkmcnt(7)
	v_mfma_f32_32x32x16_bf16 v[80:95], v[148:151], v[104:107], v[80:95]
	s_waitcnt lgkmcnt(5)
	v_mfma_f32_32x32x16_bf16 v[64:79], v[156:159], v[104:107], v[64:79]
	v_mfma_f32_32x32x16_bf16 v[80:95], v[152:155], v[108:111], v[80:95]
	ds_read2_b64 v[152:155], v252 offset0:4 offset1:6
	s_waitcnt lgkmcnt(5)
	v_mfma_f32_32x32x16_bf16 v[64:79], v[160:163], v[108:111], v[64:79]
	ds_read2_b64 v[160:163], v252 offset1:2
	ds_read2_b64 v[156:159], v253 offset0:32 offset1:34
	ds_read2_b64 v[148:151], v253 offset0:36 offset1:38
	ds_read2_b64 v[144:147], v252 offset0:8 offset1:10
	ds_read2_b64 v[140:143], v253 offset0:40 offset1:42
	ds_read2_b64 v[136:139], v252 offset0:12 offset1:14
	ds_read2_b64 v[10:13], v253 offset0:44 offset1:46
	s_waitcnt lgkmcnt(11)
	v_mfma_f32_32x32x16_bf16 v[80:95], v[222:225], v[112:115], v[80:95]
	s_waitcnt lgkmcnt(9)
	v_mfma_f32_32x32x16_bf16 v[64:79], v[230:233], v[112:115], v[64:79]
	v_mfma_f32_32x32x16_bf16 v[80:95], v[226:229], v[116:119], v[80:95]
	s_waitcnt lgkmcnt(8)
	v_mfma_f32_32x32x16_bf16 v[64:79], v[234:237], v[116:119], v[64:79]
	v_min_u32_e32 v120, 0x80ff, v120
	v_add_u32_e32 v186, 1, v184
	v_min_u32_e32 v184, 0x80ff, v184
	v_min_u32_e32 v186, 0x80ff, v186
	v_lshl_add_u32 v122, v120, 12, v238
	v_lshl_add_u32 v124, v120, 6, v239
	v_lshl_add_u32 v184, v184, 12, v174
	v_lshl_add_u32 v186, v186, 12, v174
	global_load_dwordx4 v[120:123], v122, s[98:99]
	s_nop 0
	global_load_dwordx4 v[124:127], v124, s[100:101]
	global_load_dwordx2 v[184:185], v184, s[98:99] offset:128
	global_load_dwordx2 v[186:187], v186, s[98:99] offset:128
	s_and_saveexec_b64 s[46:47], vcc
	s_cbranch_execz .LBB0_434
	v_add_u32_e32 v221, s83, v201
	v_add_u32_e32 v223, 0x60, v221
	v_add_u32_e32 v222, 64, v221
	v_cmp_le_u32_e64 s[4:5], v223, v219
	v_cmp_le_u32_e32 vcc, v222, v219
	s_nop 4
	v_cndmask_b32_e64 v64, v244, v64, s[4:5]
	v_cmp_lt_u32_e64 s[4:5], v222, v219
	v_add_u32_e32 v222, 0x61, v221
	v_cmp_le_u32_e64 s[6:7], v222, v219
	v_add_u32_e32 v222, 0x42, v221
	s_nop 0
	v_cndmask_b32_e64 v65, v244, v65, s[6:7]
	v_cmp_le_u32_e64 s[6:7], v222, v219
	v_add_u32_e32 v222, 0x62, v221
	v_cmp_le_u32_e64 s[8:9], v222, v219
	v_add_u32_e32 v222, 0x43, v221
	s_nop 0
	v_cndmask_b32_e64 v66, v244, v66, s[8:9]
	v_cmp_le_u32_e64 s[8:9], v222, v219
	v_add_u32_e32 v222, 0x63, v221
	v_cmp_le_u32_e64 s[10:11], v222, v219
	v_add_u32_e32 v222, 0x48, v221
	s_nop 0
	v_cndmask_b32_e64 v67, v244, v67, s[10:11]
	v_cmp_le_u32_e64 s[10:11], v222, v219
	v_add_u32_e32 v222, 0x68, v221
	v_cmp_le_u32_e64 s[12:13], v222, v219
	v_add_u32_e32 v222, 0x49, v221
	s_nop 0
	v_cndmask_b32_e64 v68, v244, v68, s[12:13]
	v_cmp_le_u32_e64 s[12:13], v222, v219
	v_add_u32_e32 v222, 0x69, v221
	v_cmp_le_u32_e64 s[14:15], v222, v219
	v_add_u32_e32 v222, 0x4a, v221
	s_nop 0
	v_cndmask_b32_e64 v69, v244, v69, s[14:15]
	v_cmp_le_u32_e64 s[14:15], v222, v219
	v_add_u32_e32 v222, 0x6a, v221
	v_cmp_le_u32_e64 s[16:17], v222, v219
	v_add_u32_e32 v222, 0x4b, v221
	s_nop 0
	v_cndmask_b32_e64 v70, v244, v70, s[16:17]
	v_cmp_le_u32_e64 s[16:17], v222, v219
	v_add_u32_e32 v222, 0x6b, v221
	v_cmp_le_u32_e64 s[18:19], v222, v219
	v_add_u32_e32 v222, 0x50, v221
	s_nop 0
	v_cndmask_b32_e64 v71, v244, v71, s[18:19]
	v_cmp_le_u32_e64 s[18:19], v222, v219
	v_add_u32_e32 v222, 0x70, v221
	v_cmp_le_u32_e64 s[20:21], v222, v219
	v_add_u32_e32 v222, 0x51, v221
	s_nop 0
	v_cndmask_b32_e64 v72, v244, v72, s[20:21]
	v_cmp_le_u32_e64 s[20:21], v222, v219
	v_add_u32_e32 v222, 0x71, v221
	v_cmp_le_u32_e64 s[22:23], v222, v219
	v_add_u32_e32 v222, 0x52, v221
	s_nop 0
	v_cndmask_b32_e64 v73, v244, v73, s[22:23]
	v_cmp_le_u32_e64 s[22:23], v222, v219
	v_add_u32_e32 v222, 0x72, v221
	v_cmp_le_u32_e64 s[24:25], v222, v219
	v_add_u32_e32 v222, 0x53, v221
	s_nop 0
	v_cndmask_b32_e64 v74, v244, v74, s[24:25]
	v_cmp_le_u32_e64 s[24:25], v222, v219
	v_add_u32_e32 v222, 0x73, v221
	v_cmp_le_u32_e64 s[26:27], v222, v219
	v_add_u32_e32 v222, 0x58, v221
	s_nop 0
	v_cndmask_b32_e64 v75, v244, v75, s[26:27]
	v_cmp_le_u32_e64 s[26:27], v222, v219
	v_add_u32_e32 v222, 0x78, v221
	v_cmp_le_u32_e64 s[28:29], v222, v219
	v_add_u32_e32 v222, 0x59, v221
	s_nop 0
	v_cndmask_b32_e64 v76, v244, v76, s[28:29]
	v_cmp_le_u32_e64 s[28:29], v222, v219
	v_add_u32_e32 v222, 0x79, v221
	v_cmp_le_u32_e64 s[30:31], v222, v219
	v_add_u32_e32 v222, 0x5a, v221
	s_nop 0
	v_cndmask_b32_e64 v77, v244, v77, s[30:31]
	v_cmp_le_u32_e64 s[30:31], v222, v219
	v_add_u32_e32 v222, 0x7a, v221
	v_cmp_le_u32_e64 s[34:35], v222, v219
	v_add_u32_e32 v222, 0x5b, v221
	v_add_u32_e32 v221, 0x7b, v221
	v_cndmask_b32_e64 v78, v244, v78, s[34:35]
	v_cmp_le_u32_e64 s[34:35], v222, v219
	v_cmp_gt_u32_e64 s[36:37], v221, v219
	s_and_saveexec_b64 s[40:41], s[36:37]
	v_mov_b32_e32 v79, s52
	s_or_b64 exec, exec, s[40:41]
	v_cndmask_b32_e64 v81, v244, v81, s[4:5]
	v_cndmask_b32_e32 v80, v244, v80, vcc
	v_cndmask_b32_e64 v82, v244, v82, s[6:7]
	v_cndmask_b32_e64 v83, v244, v83, s[8:9]
	v_cndmask_b32_e64 v84, v244, v84, s[10:11]
	v_cndmask_b32_e64 v85, v244, v85, s[12:13]
	v_cndmask_b32_e64 v86, v244, v86, s[14:15]
	v_cndmask_b32_e64 v87, v244, v87, s[16:17]
	v_cndmask_b32_e64 v88, v244, v88, s[18:19]
	v_cndmask_b32_e64 v89, v244, v89, s[20:21]
	v_cndmask_b32_e64 v90, v244, v90, s[22:23]
	v_cndmask_b32_e64 v91, v244, v91, s[24:25]
	v_cndmask_b32_e64 v92, v244, v92, s[26:27]
	v_cndmask_b32_e64 v93, v244, v93, s[28:29]
	v_cndmask_b32_e64 v94, v244, v94, s[30:31]
	v_cndmask_b32_e64 v95, v244, v95, s[34:35]

; #define LAS __attribute__((address_space(3)))
; __device__ __forceinline__ void qk_tile(f32x16& s0, f32x16& s1, LAS unsigned char* kb, const bf16x8 (&qr)[6], const f32x16& negm, int r32, int hi) {
;     bf16x8 kf[12];
; #pragma unroll
;     for (int ks = 0; ks < 6; ++ks) { kf[2 * ks] = *(const LAS bf16x8*)(kb + r32 * KPT + ks * 32 + hi * 16); kf[2 * ks + 1] = *(const LAS bf16x8*)(kb + (32 + r32) * KPT + ks * 32 + hi * 16); }
;     __builtin_amdgcn_sched_barrier(0);
; #pragma unroll
;     for (int ks = 0; ks < 6; ++ks) {
;         s0 = __builtin_amdgcn_mfma_f32_32x32x16_bf16(kf[2 * ks], qr[ks], ks == 0 ? negm : s0, 0, 0, 0);
;         s1 = __builtin_amdgcn_mfma_f32_32x32x16_bf16(kf[2 * ks + 1], qr[ks], ks == 0 ? negm : s1, 0, 0, 0);
;     }
.LBB0_443:
	s_add_i32 s85, s84, -3
	s_cmp_lt_u32 s85, s57
	s_cselect_b64 s[44:45], -1, 0
	s_cselect_b32 s32, 0, 1
	s_cmp_eq_u32 s43, 8
	s_cselect_b32 s32, 0, s32
	s_and_b64 s[4:5], s[44:45], exec
	s_cselect_b32 s4, 0, s79
	s_lshl_b32 s4, s4, 6
	s_sub_i32 s5, 0x80, s4
	v_add_u32_e32 v14, s83, v213
	v_add_u32_e32 v15, s83, v173
	v_cmp_le_u32_e32 vcc, s83, v220
	s_and_saveexec_b64 s[46:47], vcc
	s_cbranch_execz .Latt_sk3
	ds_read_b128 v[2:5], v241
	ds_read_b128 v[6:9], v241 offset:32
	ds_read_b128 v[10:13], v241 offset:6656
	ds_read_b128 v[136:139], v241 offset:6688
	ds_read_b128 v[140:143], v241 offset:64
	ds_read_b128 v[144:147], v241 offset:96
	ds_read_b128 v[148:151], v241 offset:6720
	ds_read_b128 v[152:155], v241 offset:6752
	ds_read_b128 v[156:159], v241 offset:128
	ds_read_b128 v[160:163], v241 offset:160
	ds_read_b128 v[222:225], v241 offset:6784
	ds_read_b128 v[226:229], v241 offset:6816
	s_waitcnt lgkmcnt(11)
	v_mfma_f32_32x32x16_bf16 v[80:95], v[2:5], v[96:99], v[48:63]
	s_add_i32 s4, s83, 63
	v_cmp_gt_i32_e32 vcc, s4, v175
	s_waitcnt lgkmcnt(9)
	v_mfma_f32_32x32x16_bf16 v[64:79], v[10:13], v[96:99], v[48:63]
	v_mfma_f32_32x32x16_bf16 v[80:95], v[6:9], v[100:103], v[80:95]
	s_waitcnt lgkmcnt(8)
	v_mfma_f32_32x32x16_bf16 v[64:79], v[136:139], v[100:103], v[64:79]
	s_waitcnt lgkmcnt(7)
	v_mfma_f32_32x32x16_bf16 v[80:95], v[140:143], v[104:107], v[80:95]
	s_waitcnt lgkmcnt(5)
	v_mfma_f32_32x32x16_bf16 v[64:79], v[148:151], v[104:107], v[64:79]
	v_mfma_f32_32x32x16_bf16 v[80:95], v[144:147], v[108:111], v[80:95]
	ds_read2_b64 v[144:147], v252 offset0:4 offset1:6
	s_waitcnt lgkmcnt(5)
	v_mfma_f32_32x32x16_bf16 v[64:79], v[152:155], v[108:111], v[64:79]
	ds_read2_b64 v[152:155], v252 offset1:2
	ds_read2_b64 v[148:151], v253 offset0:32 offset1:34
	ds_read2_b64 v[140:143], v253 offset0:36 offset1:38
	ds_read2_b64 v[136:139], v252 offset0:8 offset1:10
	ds_read2_b64 v[10:13], v253 offset0:40 offset1:42
	ds_read2_b64 v[6:9], v252 offset0:12 offset1:14
	ds_read2_b64 v[2:5], v253 offset0:44 offset1:46
	s_waitcnt lgkmcnt(11)
	v_mfma_f32_32x32x16_bf16 v[80:95], v[156:159], v[112:115], v[80:95]
	s_waitcnt lgkmcnt(9)
	v_mfma_f32_32x32x16_bf16 v[64:79], v[222:225], v[112:115], v[64:79]
	v_mfma_f32_32x32x16_bf16 v[80:95], v[160:163], v[116:119], v[80:95]
	s_waitcnt lgkmcnt(8)
	v_mfma_f32_32x32x16_bf16 v[64:79], v[226:229], v[116:119], v[64:79]
	v_add_u32_e32 v120, s5, v14
	v_add_u32_e32 v184, s5, v15
	v_min_u32_e32 v120, 0x80ff, v120
	v_add_u32_e32 v186, 1, v184
	v_min_u32_e32 v184, 0x80ff, v184
	v_min_u32_e32 v186, 0x80ff, v186
	v_lshl_add_u32 v122, v120, 12, v238
	v_lshl_add_u32 v124, v120, 6, v239
	v_lshl_add_u32 v184, v184, 12, v174
	v_lshl_add_u32 v186, v186, 12, v174
	global_load_dwordx4 v[120:123], v122, s[98:99]
	s_nop 0
	global_load_dwordx4 v[124:127], v124, s[100:101]
	global_load_dwordx2 v[184:185], v184, s[98:99] offset:128
	global_load_dwordx2 v[186:187], v186, s[98:99] offset:128
	s_cmp_eq_u32 s32, 0
	s_cbranch_scc1 .Lqp_skip_a3
	v_add_u32_e32 v156, s56, v215
	v_mad_u32_u24 v156, v156, s90, v176
	s_add_u32 s4, s48, s86
	s_addc_u32 s5, s49, 0
	s_add_u32 s6, s48, s78
	s_addc_u32 s7, s49, 0
	global_load_dwordx4 v[96:99], v156, s[4:5] nt
	global_load_dwordx4 v[100:103], v156, s[4:5] offset:32 nt
	global_load_dwordx4 v[104:107], v156, s[4:5] offset:64 nt
	global_load_dwordx4 v[108:111], v156, s[4:5] offset:96 nt
	global_load_dwordx4 v[112:115], v156, s[6:7] offset:2048 nt
	global_load_dwordx4 v[116:119], v156, s[6:7] offset:2080 nt
; __device__ __forceinline__ void sm_pv(f32x16& s0, f32x16& s1, f32x16& o0, f32x16& o1, float& m_run, float& l_run, f32x16& negm, LAS unsigned char* vb, bool domask, int kbase, int qm, int r32, int hi) {
;     ...
;     if (domask) {
;         const int kb0 = kbase + 4 * hi;
; #pragma unroll
;         for (int r = 0; r < 16; ++r) { const int kv = kb0 + (r & 3) + 8 * (r >> 2); if (kv > qm) s0[r] = -INFINITY; if (kv + 32 > qm) s1[r] = -INFINITY; }
;     }
.Lqp_skip_a3:
	s_and_saveexec_b64 s[58:59], vcc
	s_cbranch_execz .LBB0_448
	v_add_u32_e32 v156, s83, v201
	v_add_u32_e32 v157, 32, v156
	v_cmp_ge_i32_e64 s[4:5], v177, v157
	v_add_u32_e32 v157, 33, v156
	v_cmp_ge_i32_e64 s[6:7], v177, v157
	v_add_u32_e32 v157, 2, v156
	v_cmp_le_u32_e32 vcc, v156, v219
	s_nop 2
	v_cndmask_b32_e64 v65, v244, v65, s[6:7]
	v_cmp_ge_i32_e64 s[6:7], v177, v157
	v_add_u32_e32 v157, 34, v156
	v_cmp_ge_i32_e64 s[8:9], v177, v157
	v_add_u32_e32 v157, 3, v156
	v_cndmask_b32_e64 v64, v244, v64, s[4:5]
	v_cndmask_b32_e64 v66, v244, v66, s[8:9]
	v_cmp_ge_i32_e64 s[8:9], v177, v157
	v_add_u32_e32 v157, 35, v156
	v_cmp_ge_i32_e64 s[10:11], v177, v157
	v_add_u32_e32 v157, 8, v156
	v_cmp_gt_i32_e64 s[4:5], v177, v156
	v_cndmask_b32_e64 v67, v244, v67, s[10:11]
	v_cmp_ge_i32_e64 s[10:11], v177, v157
	v_add_u32_e32 v157, 40, v156
	v_cmp_ge_i32_e64 s[12:13], v177, v157
	v_add_u32_e32 v157, 9, v156
	s_nop 0
	v_cndmask_b32_e64 v68, v244, v68, s[12:13]
	v_cmp_ge_i32_e64 s[12:13], v177, v157
	v_add_u32_e32 v157, 41, v156
	v_cmp_ge_i32_e64 s[14:15], v177, v157
	v_add_u32_e32 v157, 10, v156
	s_nop 0
	v_cndmask_b32_e64 v69, v244, v69, s[14:15]
	v_cmp_ge_i32_e64 s[14:15], v177, v157
	v_add_u32_e32 v157, 42, v156
	v_cmp_ge_i32_e64 s[16:17], v177, v157
	v_add_u32_e32 v157, 11, v156
	s_nop 0
	v_cndmask_b32_e64 v70, v244, v70, s[16:17]
	v_cmp_ge_i32_e64 s[16:17], v177, v157
	v_add_u32_e32 v157, 43, v156
	v_cmp_ge_i32_e64 s[18:19], v177, v157
	v_add_u32_e32 v157, 16, v156
	s_nop 0
	v_cndmask_b32_e64 v71, v244, v71, s[18:19]
	v_cmp_ge_i32_e64 s[18:19], v177, v157
	v_add_u32_e32 v157, 48, v156
	v_cmp_ge_i32_e64 s[20:21], v177, v157
	v_add_u32_e32 v157, 17, v156
	s_nop 0
	v_cndmask_b32_e64 v72, v244, v72, s[20:21]
	v_cmp_ge_i32_e64 s[20:21], v177, v157
	v_add_u32_e32 v157, 49, v156
	v_cmp_ge_i32_e64 s[22:23], v177, v157
	v_add_u32_e32 v157, 18, v156
	s_nop 0
	v_cndmask_b32_e64 v73, v244, v73, s[22:23]
	v_cmp_ge_i32_e64 s[22:23], v177, v157
	v_add_u32_e32 v157, 50, v156
	v_cmp_ge_i32_e64 s[24:25], v177, v157
	v_add_u32_e32 v157, 19, v156
	s_nop 0
	v_cndmask_b32_e64 v74, v244, v74, s[24:25]
	v_cmp_ge_i32_e64 s[24:25], v177, v157
	v_add_u32_e32 v157, 51, v156
	v_cmp_ge_i32_e64 s[26:27], v177, v157
	v_add_u32_e32 v157, 24, v156
	s_nop 0
	v_cndmask_b32_e64 v75, v244, v75, s[26:27]
	v_cmp_ge_i32_e64 s[26:27], v177, v157
	v_add_u32_e32 v157, 56, v156
	v_cmp_ge_i32_e64 s[28:29], v177, v157
	v_add_u32_e32 v157, 25, v156
	s_nop 0
	v_cndmask_b32_e64 v76, v244, v76, s[28:29]
	v_cmp_ge_i32_e64 s[28:29], v177, v157
	v_add_u32_e32 v157, 57, v156
	v_cmp_ge_i32_e64 s[30:31], v177, v157
	v_add_u32_e32 v157, 26, v156
	s_nop 0
	v_cndmask_b32_e64 v77, v244, v77, s[30:31]
	v_cmp_ge_i32_e64 s[30:31], v177, v157
	v_add_u32_e32 v157, 58, v156
	v_cmp_ge_i32_e64 s[34:35], v177, v157
	v_add_u32_e32 v157, 27, v156
	v_add_u32_e32 v156, 59, v156
	v_cndmask_b32_e64 v78, v244, v78, s[34:35]
	v_cmp_ge_i32_e64 s[34:35], v177, v157
	v_cmp_lt_i32_e64 s[36:37], v177, v156
	s_and_saveexec_b64 s[40:41], s[36:37]
	v_mov_b32_e32 v79, s52
	s_or_b64 exec, exec, s[40:41]
	v_cndmask_b32_e32 v80, v244, v80, vcc
	v_cndmask_b32_e64 v81, v244, v81, s[4:5]
	v_cndmask_b32_e64 v82, v244, v82, s[6:7]
	v_cndmask_b32_e64 v83, v244, v83, s[8:9]
	v_cndmask_b32_e64 v84, v244, v84, s[10:11]
	v_cndmask_b32_e64 v85, v244, v85, s[12:13]
	v_cndmask_b32_e64 v86, v244, v86, s[14:15]
	v_cndmask_b32_e64 v87, v244, v87, s[16:17]
	v_cndmask_b32_e64 v88, v244, v88, s[18:19]
	v_cndmask_b32_e64 v89, v244, v89, s[20:21]
	v_cndmask_b32_e64 v90, v244, v90, s[22:23]
	v_cndmask_b32_e64 v91, v244, v91, s[24:25]
	v_cndmask_b32_e64 v92, v244, v92, s[26:27]
	v_cndmask_b32_e64 v93, v244, v93, s[28:29]
	v_cndmask_b32_e64 v94, v244, v94, s[30:31]
	v_cndmask_b32_e64 v95, v244, v95, s[34:35]

.LBB0_451:
	s_or_b64 exec, exec, s[46:47]
	s_cmp_eq_u32 s32, 0
	s_cbranch_scc1 .Lqw_t3a_n
	s_waitcnt vmcnt(13)
	s_branch .Lqw_t3a_j
.Lqw_t3a_n:
	s_waitcnt vmcnt(7)
.Lqw_t3a_j:
	ds_write_b128 v210, v[128:131] offset:13312
	s_and_saveexec_b64 s[4:5], s[2:3]
	s_cbranch_execz .LBB0_453
	s_cmp_eq_u32 s32, 0
	s_cbranch_scc1 .Lqw_t3b_n
	s_waitcnt vmcnt(12)
	s_branch .Lqw_t3b_j
.Lqw_t3b_n:
	s_waitcnt vmcnt(6)
.Lqw_t3b_j:
	ds_write_b128 v210, v[132:135] offset:13440
.LBB0_453:
	s_or_b64 exec, exec, s[4:5]
	s_cmp_eq_u32 s32, 0
	s_cbranch_scc1 .Lqw_t3c_n
	s_waitcnt vmcnt(10)
	s_branch .Lqw_t3c_j

; #define LAS __attribute__((address_space(3)))
; __device__ __forceinline__ void qk_tile(f32x16& s0, f32x16& s1, LAS unsigned char* kb, const bf16x8 (&qr)[6], const f32x16& negm, int r32, int hi) {
;     bf16x8 kf[12];
; #pragma unroll
;     for (int ks = 0; ks < 6; ++ks) { kf[2 * ks] = *(const LAS bf16x8*)(kb + r32 * KPT + ks * 32 + hi * 16); kf[2 * ks + 1] = *(const LAS bf16x8*)(kb + (32 + r32) * KPT + ks * 32 + hi * 16); }
;     __builtin_amdgcn_sched_barrier(0);
; #pragma unroll
;     for (int ks = 0; ks < 6; ++ks) {
;         s0 = __builtin_amdgcn_mfma_f32_32x32x16_bf16(kf[2 * ks], qr[ks], ks == 0 ? negm : s0, 0, 0, 0);
;         s1 = __builtin_amdgcn_mfma_f32_32x32x16_bf16(kf[2 * ks + 1], qr[ks], ks == 0 ? negm : s1, 0, 0, 0);
;     }
; }
; __device__ __forceinline__ void sm_pv(f32x16& s0, f32x16& s1, f32x16& o0, f32x16& o1, float& m_run, float& l_run, f32x16& negm, LAS unsigned char* vb, bool domask, int kbase, int qm, int r32, int hi) {
;     s16x4 vlo[8], vhh[8];
; #pragma unroll
;     for (int kk = 0; kk < 4; ++kk) { const int koff = 2 * (16 * kk + 4 * hi);
;         vlo[2 * kk] = *(const LAS s16x4*)(vb + r32 * VP + koff); vhh[2 * kk] = *(const LAS s16x4*)(vb + r32 * VP + koff + 16);
;         vlo[2 * kk + 1] = *(const LAS s16x4*)(vb + (32 + r32) * VP + koff); vhh[2 * kk + 1] = *(const LAS s16x4*)(vb + (32 + r32) * VP + koff + 16); }
;     __builtin_amdgcn_sched_barrier(0);
;     if (domask) {
;         const int kb0 = kbase + 4 * hi;
; #pragma unroll
;         for (int r = 0; r < 16; ++r) { const int kv = kb0 + (r & 3) + 8 * (r >> 2); if (kv > qm) s0[r] = -INFINITY; if (kv + 32 > qm) s1[r] = -INFINITY; }
;     }
.Lqw_t3c_j:
	v_perm_b32 v2, v190, v188, s94
	v_perm_b32 v3, v190, v188, s95
	ds_write2_b32 v254, v2, v3 offset0:128 offset1:162
	v_perm_b32 v2, v191, v189, s94
	v_perm_b32 v3, v191, v189, s95
	ds_write2_b32 v254, v2, v3 offset0:196 offset1:230
	s_waitcnt lgkmcnt(0)
	s_barrier
	s_andn2_b64 vcc, exec, s[44:45]
	s_cbranch_vccnz .LBB0_442
	s_cmp_gt_u32 s84, s57
	s_cselect_b32 s4, s79, 0
	s_lshl_b32 s4, s4, 6
	s_sub_i32 s5, 0xc0, s4
	s_add_i32 s4, s83, 64
	v_cmp_le_u32_e32 vcc, s4, v220
	s_and_saveexec_b64 s[44:45], vcc
	s_cbranch_execz .Latt_sk4
	ds_read_b128 v[2:5], v240 offset:13312
	ds_read_b128 v[6:9], v240 offset:13344
	ds_read_b128 v[10:13], v240 offset:19968
	ds_read_b128 v[136:139], v240 offset:20000
	ds_read_b128 v[140:143], v240 offset:13376
	ds_read_b128 v[144:147], v240 offset:13408
	ds_read_b128 v[148:151], v240 offset:20032
	ds_read_b128 v[152:155], v240 offset:20064
	ds_read_b128 v[156:159], v240 offset:13440
	ds_read_b128 v[160:163], v240 offset:13472
	ds_read_b128 v[222:225], v240 offset:20096
	ds_read_b128 v[226:229], v240 offset:20128
	s_waitcnt lgkmcnt(11)
	v_mfma_f32_32x32x16_bf16 v[80:95], v[2:5], v[96:99], v[48:63]
	s_add_i32 s4, s83, 0x7f
	v_cmp_gt_i32_e32 vcc, s4, v175
	s_waitcnt lgkmcnt(9)
	v_mfma_f32_32x32x16_bf16 v[64:79], v[10:13], v[96:99], v[48:63]
	v_mfma_f32_32x32x16_bf16 v[80:95], v[6:9], v[100:103], v[80:95]
	s_waitcnt lgkmcnt(8)
	v_mfma_f32_32x32x16_bf16 v[64:79], v[136:139], v[100:103], v[64:79]
	s_waitcnt lgkmcnt(7)
	v_mfma_f32_32x32x16_bf16 v[80:95], v[140:143], v[104:107], v[80:95]
	s_waitcnt lgkmcnt(5)
	v_mfma_f32_32x32x16_bf16 v[64:79], v[148:151], v[104:107], v[64:79]
	v_mfma_f32_32x32x16_bf16 v[80:95], v[144:147], v[108:111], v[80:95]
	ds_read2_b64 v[144:147], v250 offset0:68 offset1:70
	s_waitcnt lgkmcnt(5)
	v_mfma_f32_32x32x16_bf16 v[64:79], v[152:155], v[108:111], v[64:79]
	ds_read2_b64 v[152:155], v250 offset0:64 offset1:66
	ds_read2_b64 v[148:151], v251 offset0:96 offset1:98
	ds_read2_b64 v[140:143], v251 offset0:100 offset1:102
	ds_read2_b64 v[136:139], v250 offset0:72 offset1:74
	ds_read2_b64 v[10:13], v251 offset0:104 offset1:106
	ds_read2_b64 v[6:9], v250 offset0:76 offset1:78
	ds_read2_b64 v[2:5], v251 offset0:108 offset1:110
	s_waitcnt lgkmcnt(11)
	v_mfma_f32_32x32x16_bf16 v[80:95], v[156:159], v[112:115], v[80:95]
	s_waitcnt lgkmcnt(9)
	v_mfma_f32_32x32x16_bf16 v[64:79], v[222:225], v[112:115], v[64:79]
	v_mfma_f32_32x32x16_bf16 v[80:95], v[160:163], v[116:119], v[80:95]
	s_waitcnt lgkmcnt(8)
	v_mfma_f32_32x32x16_bf16 v[64:79], v[226:229], v[116:119], v[64:79]
	v_add_u32_e32 v128, s5, v14
	v_add_u32_e32 v188, s5, v15
	v_min_u32_e32 v128, 0x80ff, v128
	v_add_u32_e32 v190, 1, v188
	v_min_u32_e32 v188, 0x80ff, v188
	v_min_u32_e32 v190, 0x80ff, v190
	v_lshl_add_u32 v130, v128, 12, v238
	v_lshl_add_u32 v132, v128, 6, v239
	v_lshl_add_u32 v188, v188, 12, v174
	v_lshl_add_u32 v190, v190, 12, v174
	global_load_dwordx4 v[128:131], v130, s[98:99]
	s_nop 0
	global_load_dwordx4 v[132:135], v132, s[100:101]
	global_load_dwordx2 v[188:189], v188, s[98:99] offset:128
	global_load_dwordx2 v[190:191], v190, s[98:99] offset:128
	s_and_saveexec_b64 s[46:47], vcc
	s_cbranch_execz .LBB0_459
	v_add_u32_e32 v14, s83, v201
	v_add_u32_e32 v156, 0x60, v14
	v_add_u32_e32 v15, 64, v14
	v_cmp_le_u32_e64 s[4:5], v156, v219
	v_cmp_le_u32_e32 vcc, v15, v219
	s_nop 4
	v_cndmask_b32_e64 v64, v244, v64, s[4:5]
	v_cmp_lt_u32_e64 s[4:5], v15, v219
	v_add_u32_e32 v15, 0x61, v14
	v_cmp_le_u32_e64 s[6:7], v15, v219
	v_add_u32_e32 v15, 0x42, v14
	s_nop 0
	v_cndmask_b32_e64 v65, v244, v65, s[6:7]
	v_cmp_le_u32_e64 s[6:7], v15, v219
	v_add_u32_e32 v15, 0x62, v14
	v_cmp_le_u32_e64 s[8:9], v15, v219
	v_add_u32_e32 v15, 0x43, v14
	s_nop 0
	v_cndmask_b32_e64 v66, v244, v66, s[8:9]
	v_cmp_le_u32_e64 s[8:9], v15, v219
	v_add_u32_e32 v15, 0x63, v14
	v_cmp_le_u32_e64 s[10:11], v15, v219
	v_add_u32_e32 v15, 0x48, v14
	s_nop 0
	v_cndmask_b32_e64 v67, v244, v67, s[10:11]
	v_cmp_le_u32_e64 s[10:11], v15, v219
	v_add_u32_e32 v15, 0x68, v14
	v_cmp_le_u32_e64 s[12:13], v15, v219
	v_add_u32_e32 v15, 0x49, v14
	s_nop 0
	v_cndmask_b32_e64 v68, v244, v68, s[12:13]
	v_cmp_le_u32_e64 s[12:13], v15, v219
	v_add_u32_e32 v15, 0x69, v14
	v_cmp_le_u32_e64 s[14:15], v15, v219
	v_add_u32_e32 v15, 0x4a, v14
	s_nop 0
	v_cndmask_b32_e64 v69, v244, v69, s[14:15]
	v_cmp_le_u32_e64 s[14:15], v15, v219
	v_add_u32_e32 v15, 0x6a, v14
	v_cmp_le_u32_e64 s[16:17], v15, v219
	v_add_u32_e32 v15, 0x4b, v14
	s_nop 0
	v_cndmask_b32_e64 v70, v244, v70, s[16:17]
	v_cmp_le_u32_e64 s[16:17], v15, v219
	v_add_u32_e32 v15, 0x6b, v14
	v_cmp_le_u32_e64 s[18:19], v15, v219
	v_add_u32_e32 v15, 0x50, v14
	s_nop 0
	v_cndmask_b32_e64 v71, v244, v71, s[18:19]
	v_cmp_le_u32_e64 s[18:19], v15, v219
	v_add_u32_e32 v15, 0x70, v14
	v_cmp_le_u32_e64 s[20:21], v15, v219
	v_add_u32_e32 v15, 0x51, v14
	s_nop 0
	v_cndmask_b32_e64 v72, v244, v72, s[20:21]
	v_cmp_le_u32_e64 s[20:21], v15, v219
	v_add_u32_e32 v15, 0x71, v14
	v_cmp_le_u32_e64 s[22:23], v15, v219
	v_add_u32_e32 v15, 0x52, v14
	s_nop 0
	v_cndmask_b32_e64 v73, v244, v73, s[22:23]
	v_cmp_le_u32_e64 s[22:23], v15, v219
	v_add_u32_e32 v15, 0x72, v14
	v_cmp_le_u32_e64 s[24:25], v15, v219
	v_add_u32_e32 v15, 0x53, v14
	s_nop 0
	v_cndmask_b32_e64 v74, v244, v74, s[24:25]
	v_cmp_le_u32_e64 s[24:25], v15, v219
	v_add_u32_e32 v15, 0x73, v14
	v_cmp_le_u32_e64 s[26:27], v15, v219
	v_add_u32_e32 v15, 0x58, v14
	s_nop 0
	v_cndmask_b32_e64 v75, v244, v75, s[26:27]
	v_cmp_le_u32_e64 s[26:27], v15, v219
	v_add_u32_e32 v15, 0x78, v14
	v_cmp_le_u32_e64 s[28:29], v15, v219
	v_add_u32_e32 v15, 0x59, v14
	s_nop 0
	v_cndmask_b32_e64 v76, v244, v76, s[28:29]
	v_cmp_le_u32_e64 s[28:29], v15, v219
	v_add_u32_e32 v15, 0x79, v14
	v_cmp_le_u32_e64 s[30:31], v15, v219
	v_add_u32_e32 v15, 0x5a, v14
	s_nop 0
	v_cndmask_b32_e64 v77, v244, v77, s[30:31]
	v_cmp_le_u32_e64 s[30:31], v15, v219
	v_add_u32_e32 v15, 0x7a, v14
	v_cmp_le_u32_e64 s[34:35], v15, v219
	v_add_u32_e32 v15, 0x5b, v14
	v_add_u32_e32 v14, 0x7b, v14
	v_cndmask_b32_e64 v78, v244, v78, s[34:35]
	v_cmp_le_u32_e64 s[34:35], v15, v219
	v_cmp_gt_u32_e64 s[36:37], v14, v219
	s_and_saveexec_b64 s[40:41], s[36:37]
	v_mov_b32_e32 v79, s52
	s_or_b64 exec, exec, s[40:41]
	v_cndmask_b32_e64 v81, v244, v81, s[4:5]
	v_cndmask_b32_e32 v80, v244, v80, vcc
	v_cndmask_b32_e64 v82, v244, v82, s[6:7]
	v_cndmask_b32_e64 v83, v244, v83, s[8:9]
	v_cndmask_b32_e64 v84, v244, v84, s[10:11]
	v_cndmask_b32_e64 v85, v244, v85, s[12:13]
	v_cndmask_b32_e64 v86, v244, v86, s[14:15]
	v_cndmask_b32_e64 v87, v244, v87, s[16:17]
	v_cndmask_b32_e64 v88, v244, v88, s[18:19]
	v_cndmask_b32_e64 v89, v244, v89, s[20:21]
	v_cndmask_b32_e64 v90, v244, v90, s[22:23]
	v_cndmask_b32_e64 v91, v244, v91, s[24:25]
	v_cndmask_b32_e64 v92, v244, v92, s[26:27]
	v_cndmask_b32_e64 v93, v244, v93, s[28:29]
	v_cndmask_b32_e64 v94, v244, v94, s[30:31]
	v_cndmask_b32_e64 v95, v244, v95, s[34:35]

; #define LAS __attribute__((address_space(3)))
; __device__ __forceinline__ unsigned cvtpk(float lo, float hi) { const f32x2 v = {lo, hi}; const bf16x2_t b = __builtin_convertvector(v, bf16x2_t); return __builtin_bit_cast(unsigned, b); }
; __device__ __forceinline__ void attn_phase(LAS unsigned char* lds, KP kp, int wid0) {
;     ...
;             if (j < 8) { const int qn = 16 + 256 * j + 32 * wid + r32; ATT_LOADQ(qn); }
;             { const auto rr = __builtin_amdgcn_permlane32_swap(__float_as_uint(l_run), __float_as_uint(l_run), false, false); l_run = __uint_as_float(rr[0]) + __uint_as_float(rr[1]); }
;             {
;                 const float inv = 1.0f / l_run;
;                 LAS unsigned char* stg = lds + 45056 + wid * 4608;
; #pragma unroll
;                 for (int g = 0; g < 4; ++g) {
;                     u32x2 w; w.x = cvtpk(o0[4 * g] * inv, o0[4 * g + 1] * inv); w.y = cvtpk(o0[4 * g + 2] * inv, o0[4 * g + 3] * inv); *(LAS u32x2*)(stg + r32 * 144 + (8 * g + 4 * hi) * 2) = w;
;                     w.x = cvtpk(o1[4 * g] * inv, o1[4 * g + 1] * inv); w.y = cvtpk(o1[4 * g + 2] * inv, o1[4 * g + 3] * inv); *(LAS u32x2*)(stg + r32 * 144 + 64 + (8 * g + 4 * hi) * 2) = w;
;                 }
;                 asm volatile("s_waitcnt lgkmcnt(0)" ::: "memory");
; #pragma unroll
;                 for (int i = 0; i < 4; ++i) {
;                     const int row = i * 8 + (lane >> 3), ch = lane & 7, qq = qw0 + row;
;                     const u32x4 v = *(const LAS u32x4*)(stg + row * 144 + ch * 16);
;                     if (qq >= 0) *(u32x4*)(O + (size_t)(rowb + qq) * DM + h * 64 + ch * 8) = v;
;                 }
.LBB0_466:
.LBB0_467:
	v_mov_b32_e32 v1, v218
	s_nop 1
	v_permlane32_swap_b32_e32 v218, v1
	v_add_f32_e32 v1, v218, v1
	v_div_scale_f32 v10, s[4:5], v1, v1, 1.0
	v_rcp_f32_e32 v11, v10
	s_nop 0
	v_fma_f32 v12, -v10, v11, 1.0
	v_fmac_f32_e32 v11, v12, v11
	v_div_scale_f32 v12, vcc, 1.0, v1, 1.0
	v_mul_f32_e32 v13, v12, v11
	v_fma_f32 v48, -v10, v13, v12
	v_fmac_f32_e32 v13, v48, v11
	v_fma_f32 v10, -v10, v13, v12
	v_div_fmas_f32 v10, v10, v11, v13
	v_div_fixup_f32 v10, v10, v1, 1.0
	v_pk_mul_f32 v[12:13], v[32:33], v[10:11] op_sel_hi:[1,0]
	v_pk_mul_f32 v[32:33], v[34:35], v[10:11] op_sel_hi:[1,0]
	v_pk_mul_f32 v[16:17], v[16:17], v[10:11] op_sel_hi:[1,0]
	v_pk_mul_f32 v[18:19], v[18:19], v[10:11] op_sel_hi:[1,0]
	v_cvt_pk_bf16_f32 v12, v12, v13
	v_cvt_pk_bf16_f32 v13, v32, v33
	v_cvt_pk_bf16_f32 v16, v16, v17
	v_cvt_pk_bf16_f32 v17, v18, v19
	v_pk_mul_f32 v[18:19], v[36:37], v[10:11] op_sel_hi:[1,0]
	v_pk_mul_f32 v[32:33], v[38:39], v[10:11] op_sel_hi:[1,0]
	v_cvt_pk_bf16_f32 v18, v18, v19
	v_cvt_pk_bf16_f32 v19, v32, v33
	v_add_u32_e32 v1, 0xb000, v209
	ds_write2_b64 v1, v[12:13], v[18:19] offset1:2
	v_pk_mul_f32 v[12:13], v[20:21], v[10:11] op_sel_hi:[1,0]
	v_pk_mul_f32 v[18:19], v[22:23], v[10:11] op_sel_hi:[1,0]
	v_cvt_pk_bf16_f32 v12, v12, v13
	v_cvt_pk_bf16_f32 v13, v18, v19
	ds_write2_b64 v1, v[16:17], v[12:13] offset0:8 offset1:10
	v_pk_mul_f32 v[12:13], v[40:41], v[10:11] op_sel_hi:[1,0]
	v_pk_mul_f32 v[16:17], v[42:43], v[10:11] op_sel_hi:[1,0]
	v_cvt_pk_bf16_f32 v12, v12, v13
	v_cvt_pk_bf16_f32 v13, v16, v17
	v_pk_mul_f32 v[16:17], v[24:25], v[10:11] op_sel_hi:[1,0]
	v_pk_mul_f32 v[18:19], v[26:27], v[10:11] op_sel_hi:[1,0]
	v_cvt_pk_bf16_f32 v16, v16, v17
	v_cvt_pk_bf16_f32 v17, v18, v19
	v_pk_mul_f32 v[18:19], v[44:45], v[10:11] op_sel_hi:[1,0]
	v_pk_mul_f32 v[20:21], v[46:47], v[10:11] op_sel_hi:[1,0]
	v_cvt_pk_bf16_f32 v18, v18, v19
	v_cvt_pk_bf16_f32 v19, v20, v21
	ds_write2_b64 v1, v[12:13], v[18:19] offset0:4 offset1:6
	v_pk_mul_f32 v[12:13], v[28:29], v[10:11] op_sel_hi:[1,0]
	v_pk_mul_f32 v[10:11], v[30:31], v[10:11] op_sel_hi:[1,0]
	v_cvt_pk_bf16_f32 v12, v12, v13
	v_cvt_pk_bf16_f32 v13, v10, v11
	ds_write2_b64 v1, v[16:17], v[12:13] offset0:12 offset1:14
	s_waitcnt lgkmcnt(0)
	v_cmp_lt_i32_e32 vcc, -1, v175
	s_and_saveexec_b64 s[4:5], vcc
	s_cbranch_execz .LBB0_469
	v_add_u32_e32 v10, v216, v175
	v_ashrrev_i32_e32 v11, 31, v10
	v_lshlrev_b64 v[10:11], 11, v[10:11]
	v_lshl_add_u64 v[16:17], v[180:181], 0, v[10:11]
	ds_read_b128 v[10:13], v212 offset:45056
	s_waitcnt lgkmcnt(0)
	global_store_dwordx4 v[16:17], v[10:13], off
	s_nop 1
	v_add_u32_e32 v10, v217, v175
	v_ashrrev_i32_e32 v11, 31, v10
	v_lshlrev_b64 v[10:11], 11, v[10:11]
	v_lshl_add_u64 v[16:17], v[180:181], 0, v[10:11]
	ds_read_b128 v[10:13], v212 offset:46208
	s_waitcnt lgkmcnt(0)
	global_store_dwordx4 v[16:17], v[10:13], off

; __device__ __forceinline__ void attn_phase(LAS unsigned char* lds, KP kp, int wid0) {
;     ...
;         for (int j = 0; j < 9; ++j) {
;             const int q0 = j == 0 ? -240 : 16 + 256 * (j - 1);
;             const int NT = (q0 + 256 + 63) >> 6;
;             const int qw0 = q0 + 32 * wid, q = qw0 + r32, qm = q < 0 ? 0 : q;
;             const int qwmax = (qw0 + 31) < 0 ? 0 : (qw0 + 31), qwmin = qw0 < 0 ? 0 : qw0;
;             float m_run = 0.f, l_run = 0.f;
;             f32x16 o0 = {}, o1 = {}, negm = {};
;             if ((j & 1) == 0) {
;                 for (int kt2 = 0; kt2 < NT; kt2 += 2) { ATT_ITER(kt2, A, B, 0); if (kt2 + 1 < NT) ATT_ITER(kt2 + 1, B, A, 0); }
.LBB0_475:
	s_cmp_eq_u32 s32, 0
	s_cbranch_scc1 .Lqw_x_n
	s_waitcnt vmcnt(6)
	s_branch .Lqw_x_j

; __device__ __forceinline__ void attn_phase(LAS unsigned char* lds, KP kp, int wid0) {
;     ...
;         for (int j = 0; j < 9; ++j) {
;             const int q0 = j == 0 ? -240 : 16 + 256 * (j - 1);
;             const int NT = (q0 + 256 + 63) >> 6;
;             const int qw0 = q0 + 32 * wid, q = qw0 + r32, qm = q < 0 ? 0 : q;
;             const int qwmax = (qw0 + 31) < 0 ? 0 : (qw0 + 31), qwmin = qw0 < 0 ? 0 : qw0;
;             float m_run = 0.f, l_run = 0.f;
;             f32x16 o0 = {}, o1 = {}, negm = {};
;             if ((j & 1) == 0) {
;                 for (int kt2 = 0; kt2 < NT; kt2 += 2) { ATT_ITER(kt2, A, B, 0); if (kt2 + 1 < NT) ATT_ITER(kt2 + 1, B, A, 0); }
.Lqw_x_j:
	v_mov_b64_e32 v[2:3], v[128:129]
	v_mov_b64_e32 v[6:7], v[132:133]
	v_mov_b64_e32 v[4:5], v[130:131]
	v_mov_b64_e32 v[8:9], v[134:135]
	v_mov_b64_e32 v[14:15], v[188:189]
	v_mov_b64_e32 v[192:193], v[190:191]
	s_cmp_eq_u32 s43, 8
	s_cbranch_scc0 .LBB0_466
	s_branch .LBB0_467
